# grid barrier leader path: closing wait on the release atomics dropped
# speedup vs baseline: 1.0096x; 1.0070x over previous
; __device__ __forceinline__ unsigned xb_ld(unsigned* p)              { return __hip_atomic_load(p, __ATOMIC_RELAXED, __HIP_MEMORY_SCOPE_AGENT); }
; #define XB_SPIN(cond, bar) do { unsigned _sp = 0; while (cond) { __builtin_amdgcn_s_sleep(1); \
;     if ((++_sp & 255u) == 0u) { if (xb_ld(&(bar)[XB_TMO])) break; if (_sp > XB_SPIN_CAP) { atomicAdd(&(bar)[XB_TMO], 1u); break; } } } } while (0)
; __device__ __forceinline__ void xcd_barrier(const XcdBarrier& b) {
;     ...
;             asm volatile("s_waitcnt vmcnt(0)" ::: "memory");
;         } else {
;             XB_SPIN(xb_ld(&bar[XB_XGEN(b.x)]) == gen, bar);
;             __builtin_amdgcn_fence(__ATOMIC_ACQUIRE, "agent");
;             asm volatile("s_waitcnt vmcnt(0)" ::: "memory");
;         }
;     }
;     __syncthreads();
; __device__ __forceinline__ void rowwise_phase(const Args& a, LAS unsigned char* lds, bool from_partials, bool has_y, bool has_h, bool xin_bf, int xout_mode, ...
;     ...
;     for (int tile = blockIdx.x; tile < T / 256; tile += gridDim.x) {
;         const int b = tile / (SEQ / 256);
;         __syncthreads();
;         for (int col = tid; col < DM; col += 512) {
;             if (from_partials) {
;                 if (has_y) vec[col] = mod_val(a, l_y, b, gate_idx, col) * g_post[col];
;                 if (has_h) { vec[DM + col] = g_pre[col] * (1.0f + mod_val(a, l_h, b, scale_idx, col)); vec[2 * DM + col] = mod_val(a, l_h, b, shift_idx, col); }
.Lxb_norel_0:
.LBB0_99:
	s_or_b64 exec, exec, s[16:17]
.LBB0_100:
	s_or_b64 exec, exec, s[0:1]
	v_readlane_b32 s0, v246, 7
	v_readlane_b32 s1, v246, 8
	v_mov_b32_e32 v40, v192
	s_and_b64 vcc, exec, s[0:1]
	v_mbcnt_lo_u32_b32 v56, -1, 0
	s_waitcnt lgkmcnt(0)
	s_barrier
	v_writelane_b32 v245, s48, 24
	s_cbranch_vccz .LBB0_117
	v_lshlrev_b32_e32 v1, 5, v40
	v_and_b32_e32 v1, 0x7e0, v1
	v_add_u32_e32 v57, 0, v1
	v_max_i32_e32 v1, 0x200, v40
	v_sub_u32_e32 v1, v1, v40
	s_movk_i32 s0, 0x400
	v_ashrrev_i32_e32 v0, 4, v40
	v_add_u32_e32 v1, 0x1ff, v1
	v_lshlrev_b32_e32 v58, 2, v40
	v_cmp_gt_i32_e64 s[36:37], s0, v40
	v_and_b32_e32 v0, -4, v0
	s_movk_i32 s0, 0x100
	v_lshrrev_b32_e32 v2, 9, v1
	v_add_u32_e32 v3, 0, v58
	v_cmp_gt_i32_e64 s[38:39], s0, v0
	v_add_u32_e32 v5, 1, v2
	s_movk_i32 s0, 0x5ff
	v_lshl_add_u32 v2, v2, 11, v3
	v_add_u32_e32 v59, 0x1000, v3
	v_add_u32_e32 v4, 0x2000, v3
	v_cmp_lt_u32_e32 vcc, s0, v1
	v_add_u32_e32 v3, 0x1000, v2
	v_cmp_gt_u32_e64 s[40:41], 2.0, v1
	v_add_u32_e32 v1, 0x2000, v2
	v_cmp_lt_u32_e64 s[0:1], v3, v59
	v_cmp_lt_u32_e64 s[42:43], v1, v4
	s_or_b64 s[0:1], s[42:43], s[0:1]
	v_ashrrev_i32_e32 v1, 31, v0
	s_xor_b64 s[0:1], s[0:1], -1
	v_subrev_u32_e32 v62, 32, v0
	v_lshlrev_b64 v[2:3], 12, v[0:1]
	v_and_b32_e32 v4, 63, v40
	v_lshlrev_b64 v[0:1], 11, v[0:1]
	s_and_b64 s[0:1], s[0:1], s[40:41]
	v_lshl_or_b32 v0, v4, 4, v0
	v_and_b32_e32 v60, 0xfffffe, v5
	s_and_b64 s[14:15], vcc, s[0:1]
	v_lshl_or_b32 v2, v4, 5, v2
	v_lshl_add_u64 v[0:1], s[94:95], 0, v[0:1]
	s_mov_b64 s[0:1], 0x32000000
	s_movk_i32 s4, 0x1000
	v_lshl_add_u32 v61, v60, 9, v40
	v_add_u32_e32 v41, 0x200, v40
	v_cmp_ne_u32_e64 s[40:41], v5, v60
	v_lshl_add_u64 v[42:43], s[56:57], 0, v[2:3]
	v_lshl_add_u64 v[44:45], v[0:1], 0, s[0:1]
	s_mov_b32 s5, 0x30000
	s_mov_b32 s30, 0x60000
	s_mov_b32 s31, 0x90000
	s_mov_b32 s34, 0xc0000
	s_mov_b32 s35, 0xf0000
	s_mov_b32 s42, 0x120000
	s_mov_b32 s43, 0x150000
	s_mov_b32 s44, 0x180000
	s_mov_b32 s45, 0x1b0000
	s_mov_b32 s46, 0x1e0000
	s_mov_b32 s47, 0x210000
	s_mov_b32 s48, 0x240000
	s_mov_b32 s49, 0x270000
	s_mov_b32 s50, 0x2a0000
	s_mov_b32 s51, 0x2d0000
	s_mov_b32 s52, 0x300000
	s_mov_b32 s53, 0x330000
	s_mov_b32 s54, 0x360000
	s_mov_b32 s55, 0x390000
	s_mov_b32 s56, 0x3c0000
	s_mov_b32 s57, 0x3f0000
	s_mov_b32 s58, 0x420000
	s_mov_b32 s59, 0x450000
	s_mov_b32 s60, 0x480000
	s_mov_b32 s61, 0x4b0000
	s_mov_b32 s62, 0x4e0000
	s_mov_b32 s63, 0x510000
	s_mov_b32 s64, 0x540000
	s_mov_b32 s65, 0x570000
	s_mov_b32 s66, 0x5a0000
	s_mov_b32 s67, 0x5d0000
	v_mov_b32_e32 v63, 0x358637bd
	v_mbcnt_hi_u32_b32 v64, -1, v56
	s_mov_b32 s18, s2
	s_branch .LBB0_103

; __device__ __forceinline__ void xcd_barrier(const XcdBarrier& b) {
;     ...
;             asm volatile("s_waitcnt vmcnt(0)" ::: "memory");
;         }
;     }
;     __syncthreads();
; __global__ void __launch_bounds__(512, 2) fwd_kernel(Args a) {
;     ...
;     unsigned char* ws = a.ws;
;     bf16* H = (bf16*)(ws + WS_H); bf16* MIX = (bf16*)(ws + WS_MIX); bf16* PROJ = (bf16*)(ws + WS_PROJ);
;     bf16* CONCAT = (bf16*)(ws + WS_CONCAT); bf16* ACT = (bf16*)(ws + WS_ACT);
;     const float* cs = (const float*)(ws + WS_CS); bf16* XA = (bf16*)(ws + WS_XA); bf16* XB = (bf16*)(ws + WS_XB);
.Lxb_norel_1:
.LBB0_172:
	s_or_b64 exec, exec, s[14:15]
.LBB0_173:
	v_writelane_b32 v245, s82, 25
	s_nop 1
	v_writelane_b32 v245, s83, 26
	s_or_b64 exec, exec, s[0:1]
	s_lshl_b32 s1, s2, 5
	s_bfe_u32 s0, s2, 0x50003
	s_or_b32 s3, s0, s1
	s_and_b32 s4, s1, 0x80
	s_and_b32 s5, s2, 0xffffff00
	s_lshl_b32 s8, s3, 1
	s_cmpk_eq_i32 s96, 0x100
	v_writelane_b32 v245, s1, 27
	s_cselect_b64 s[0:1], -1, 0
	s_and_b64 s[0:1], s[0:1], exec
	s_cselect_b32 s8, s8, s2
	s_or_b32 s4, s4, s5
	s_cmpk_eq_i32 s96, 0x100
	s_cselect_b64 s[0:1], -1, 0
	s_and_b64 s[0:1], s[0:1], exec
	s_cselect_b32 s4, s4, s2
	s_lshr_b32 s5, s2, 1
	s_cmpk_eq_i32 s96, 0x100
	s_cselect_b64 s[80:81], -1, 0
	s_and_b64 s[0:1], s[80:81], exec
	s_cselect_b32 s0, s3, s5
	s_add_u32 s97, s94, 0x4000000
	s_addc_u32 s29, s95, 0
	s_add_u32 s82, s94, 0xc000000
	s_addc_u32 s83, s95, 0
	s_add_u32 s74, s94, 0x14000000
	s_addc_u32 s75, s95, 0
	s_add_u32 s24, s94, 0x1e000000
	s_addc_u32 s25, s95, 0
	s_cmpk_lt_i32 s2, 0x500
	s_cselect_b64 s[14:15], -1, 0
	s_ashr_i32 s27, s2, 31
	s_lshr_b32 s1, s27, 29
	v_writelane_b32 v245, s14, 28
	s_add_i32 s1, s2, s1
	s_ashr_i32 s3, s96, 31
	v_writelane_b32 v245, s15, 29
	s_ashr_i32 s14, s1, 3
	s_and_b32 s1, s1, -8
	s_sub_i32 s15, s2, s1
	s_waitcnt lgkmcnt(0)
;     __device__ bool next(int i, Unit& u) const { if (hot) { if (i >= rounds) return false; u.pm = (c % 8) * 2 + ((c / 8) & 1); u.pn = ((c / 8) >> 1) & 3; return true; } return so.next(i, u); }
; #define SEAM() do { for (int rs_ = 0; rs_ < REP_S; ++rs_) xcd_barrier(bar); } while (0)
;     __host__ __device__ bool next(int i, Unit& u) const {
;         const long L = (long)i * G + c; if (L >= nwg) return false;
;         int wgid = (int)L; { const int q = nwg / NXCD, r = nwg % NXCD, xcd = wgid % NXCD, off = wgid / NXCD; wgid = (xcd < r ? xcd * (q + 1) : r * (q + 1) + (xcd - r) * q) + off; }
;         const int nig = WGM * nN, gid = wgid / nig, fm = gid * WGM, gsz = (nM - fm) < WGM ? (nM - fm) : WGM;
;         u.pm = fm + ((wgid % nig) % gsz); u.pn = (wgid % nig) / gsz; if (rev) u.pm = nM - 1 - u.pm; return true;
; __global__ void __launch_bounds__(512, 2) fwd_kernel(Args a) {
;     ...
;     for (int l = 0; l < DEPTH; ++l) {
;         unsigned char* wl = ws + WS_W + (size_t)l * W_LAYER;
;         for (int rep = 0; rep < REP_IN; ++rep) {
;             pg8::Gemm g{H, (const bf16*)(wl + W_IN), T, INW, DM}; pg8::StaticOrder S; S.init(T, INW, gridDim.x, blockIdx.x);
;             pg8::EpiInProj E{PROJ, a.b_in + l * INW, cs};
;             pg8::gemm_phase<pg8::EpiInProj, pg8::StaticOrder, true, true>(lds, g, S, E);
;         }
;         SEAM();
;         for (int rep = 0; rep < REP_A; ++rep) attn_phase(lds, PROJ, CONCAT, a.sinks + l * 8);
;         for (int rep = 0; rep < REP_PL; ++rep) pool_phase(lds, PROJ, CONCAT);
;         SEAM();
;         for (int rep = 0; rep < REP_G; ++rep) {
;             pg8::Gemm g{CONCAT, (const bf16*)(wl + W_OUT), T, DM, DM}; pg8::StaticOrder S; S.init(T, DM, gridDim.x, blockIdx.x);
;             pg8::EpiBf16<0> E{MIX, DM, nullptr, 0, 0, 1.f};
;             pg8::gemm_phase<pg8::EpiBf16<0>, pg8::StaticOrder, true, true>(lds, g, S, E);
	v_cndmask_b32_e64 v0, 0, 1, s[80:81]
	s_cmpk_lt_i32 s2, 0x400
	s_cselect_b64 s[16:17], -1, 0
	v_readfirstlane_b32 s1, v0
	s_and_b32 s9, s0, 63
	s_ashr_i32 s0, s4, 7
	v_writelane_b32 v245, s16, 30
	s_lshr_b32 s5, s2, s1
	s_ashr_i32 s1, s0, 31
	v_writelane_b32 v245, s17, 31
	s_lshl_b64 s[16:17], s[0:1], 13
	s_lshl_b32 s0, s9, 7
	s_cmp_lg_u32 s9, 0
	s_cselect_b64 s[18:19], -1, 0
	v_writelane_b32 v245, s18, 32
	s_or_b32 s0, s16, s0
	s_add_u32 s0, s0, 0xffffff80
	v_writelane_b32 v245, s19, 33
	v_writelane_b32 v245, s16, 34
	s_addc_u32 s1, s17, -1
	s_mov_b32 s77, 0
	v_writelane_b32 v245, s17, 35
	v_writelane_b32 v245, s0, 36
	s_mov_b32 s78, s77
	s_mov_b32 s79, s77
	v_writelane_b32 v245, s1, 37
	s_lshl_b32 s0, s5, 7
	s_and_b32 s0, s0, 0x80
	s_add_u32 s0, s74, s0
	s_addc_u32 s1, s75, 0
	v_writelane_b32 v245, s0, 38
	s_lshl_b32 s84, s96, 3
	s_mov_b32 s76, s77
	v_writelane_b32 v245, s1, 39
	s_lshl_b32 s0, s5, 2
	s_and_b32 s0, s0, 4
	v_writelane_b32 v245, s0, 40
	s_lshl_b32 s0, s8, 6
	s_and_b32 s0, s0, 0x1f80
	v_writelane_b32 v245, s0, 41
	s_lshl_b32 s0, s15, 7
	s_add_u32 s1, s94, 0x802000
	v_writelane_b32 v245, s1, 42
	s_addc_u32 s1, s95, 0
	s_cmpk_lt_i32 s2, 0x1600
	v_writelane_b32 v245, s1, 43
	s_cselect_b64 s[4:5], -1, 0
	v_writelane_b32 v245, s4, 44
	s_cmp_lt_i32 s15, 0
	s_mul_i32 s1, s15, 0x81
	v_writelane_b32 v245, s5, 45
	s_movk_i32 s4, 0xa1
	s_cselect_b32 s4, s4, 0xa0
	s_mul_i32 s4, s15, s4
	s_cselect_b32 s1, s1, s0
	s_movk_i32 s0, 0x2c1
	s_cselect_b32 s16, s0, 0x2c0
	s_add_i32 s4, s4, s14
	s_mul_hi_i32 s0, s4, 0x66666667
	s_lshr_b32 s5, s0, 31
	s_ashr_i32 s0, s0, 3
	s_add_i32 s0, s0, s5
	s_mul_i32 s5, s0, 20
	s_sub_i32 s4, s4, s5
	s_lshl_b32 s8, s0, 2
	s_bfe_i32 s0, s4, 0x80000
	s_bfe_u32 s0, s0, 0x2000d
	s_add_i32 s5, s4, s0
	s_bfe_i32 s0, s5, 0x80000
	s_and_b32 s5, s5, 0xfc
	s_sub_i32 s4, s4, s5
	s_sext_i32_i16 s9, s0
	s_sext_i32_i8 s4, s4
	s_add_i32 s20, s8, s4
	s_ashr_i32 s4, s9, 2
	s_add_i32 s1, s1, s14
	v_writelane_b32 v245, s4, 46
	s_ashr_i32 s4, s1, 31
	s_lshr_b32 s4, s4, 28
	s_add_i32 s4, s1, s4
	s_ashr_i32 s5, s4, 4
	s_and_b32 s4, s4, 0xfff0
	s_sub_i32 s1, s1, s4
	s_bfe_i32 s4, s1, 0x80000
	s_bfe_u32 s4, s4, 0x2000d
	s_lshl_b32 s17, s5, 2
	s_add_i32 s5, s1, s4
	s_and_b32 s18, s5, 0xfc
	s_bfe_i32 s4, s5, 0x80000
	s_sub_i32 s5, s1, s18
	s_sext_i32_i16 s8, s4
	s_sext_i32_i8 s5, s5
	s_add_i32 s22, s17, s5
	s_ashr_i32 s5, s8, 2
	s_lshr_b32 s4, s8, 2
	v_writelane_b32 v245, s5, 47
	s_mov_b32 s8, s22
	s_lshr_b32 s0, s9, 2
	v_writelane_b32 v245, s8, 48
	s_bfe_i64 s[4:5], s[4:5], 0x100000
	s_ashr_i32 s23, s22, 31
	v_writelane_b32 v245, s9, 49
	s_lshl_b64 s[4:5], s[4:5], 19
	s_lshl_b64 s[8:9], s[22:23], 19
	v_writelane_b32 v245, s4, 50
	v_mov_b64_e32 v[206:207], s[78:79]
	s_movk_i32 s87, 0x1600
	v_writelane_b32 v245, s5, 51
	s_add_u32 s4, s24, s8
	s_addc_u32 s5, s25, s9
	s_add_u32 s8, s4, 0x40000
	v_writelane_b32 v245, s4, 52
	s_addc_u32 s9, s5, 0
	v_mov_b32_e32 v1, 0
	v_writelane_b32 v245, s5, 53
	s_mul_i32 s4, s15, s16
	s_add_i32 s4, s4, s14
	v_writelane_b32 v245, s8, 54
	s_mul_hi_i32 s5, s4, 0x2e8ba2e9
	v_mov_b32_e32 v193, 1
	v_writelane_b32 v245, s9, 55
	s_lshr_b32 s8, s5, 31
	s_ashr_i32 s5, s5, 4
	s_add_i32 s5, s5, s8
	s_lshl_b32 s8, s5, 2
	s_mulk_i32 s5, 0x58
	s_sub_i32 s5, s4, s5
	s_bfe_i32 s4, s5, 0x80000
	s_bfe_u32 s4, s4, 0x2000d
	s_add_i32 s9, s5, s4
	s_bfe_i32 s4, s9, 0x80000
	s_and_b32 s9, s9, 0xfc
	s_sub_i32 s5, s5, s9
	s_sext_i32_i16 s14, s4
	s_sext_i32_i8 s5, s5
	s_add_i32 s22, s8, s5
	s_ashr_i32 s5, s14, 2
	s_lshr_b32 s4, s14, 2
	v_writelane_b32 v245, s5, 56
	s_mov_b32 s8, s22
	v_writelane_b32 v245, s8, 57
	s_bfe_i64 s[4:5], s[4:5], 0x100000
	s_ashr_i32 s23, s22, 31
	v_writelane_b32 v245, s9, 58
	s_lshl_b64 s[4:5], s[4:5], 19
	s_lshl_b64 s[8:9], s[22:23], 19
	v_writelane_b32 v245, s4, 59
	v_mov_b64_e32 v[204:205], s[76:77]
	v_mov_b32_e32 v194, 0x358637bd
	v_writelane_b32 v245, s5, 60
	s_add_u32 s4, s97, s8
	s_addc_u32 s5, s29, s9
	s_add_u32 s8, s4, 0x40000
	v_writelane_b32 v245, s4, 61
	s_addc_u32 s9, s5, 0
	s_sub_i32 s1, s18, s1
	s_sext_i32_i8 s1, s1
	v_writelane_b32 v245, s5, 62
	s_sub_i32 s1, s1, s17
	v_writelane_b32 v245, s8, 63
	s_add_i32 s4, s1, 0xff
	s_mul_hi_i32 s1, s4, 0x160000
	v_writelane_b32 v244, s9, 0
	v_writelane_b32 v244, s4, 1
	s_mul_i32 s4, s4, 0x160000
	s_add_u32 s4, s74, s4
	s_addc_u32 s5, s75, s1
	s_add_u32 s8, s4, 0xb0000
	v_writelane_b32 v244, s4, 2
	s_addc_u32 s9, s5, 0
	s_bfe_i64 s[0:1], s[0:1], 0x100000
	v_writelane_b32 v244, s5, 3
	v_writelane_b32 v244, s8, 4
	s_mov_b32 s4, s20
	s_ashr_i32 s21, s20, 31
	v_writelane_b32 v244, s9, 5
	v_writelane_b32 v244, s4, 6
	s_lshl_b64 s[0:1], s[0:1], 19
	v_mov_b64_e32 v[162:163], 0x500
	v_writelane_b32 v244, s5, 7
	s_lshl_b64 s[4:5], s[20:21], 19
	v_writelane_b32 v244, s0, 8
	v_mov_b64_e32 v[164:165], 0x4ff
	v_mov_b32_e32 v195, 0xa00
	v_writelane_b32 v244, s1, 9
	s_add_u32 s0, s97, s4
	s_addc_u32 s1, s29, s5
	s_add_u32 s4, s0, 0x40000
	v_writelane_b32 v244, s0, 10
	s_addc_u32 s5, s1, 0
	s_lshl_b32 s86, s96, 4
	v_writelane_b32 v244, s1, 11
	v_writelane_b32 v244, s4, 12
	s_lshl_b32 s0, s96, 5
	v_mbcnt_hi_u32_b32 v196, -1, v56
	v_writelane_b32 v244, s5, 13
	v_writelane_b32 v244, s0, 14
	s_add_u32 s0, s94, 0x805000
	v_writelane_b32 v244, s0, 15
	s_addc_u32 s0, s95, 0
	v_writelane_b32 v244, s0, 16
	s_add_u32 s0, s94, 0x801000
	s_addc_u32 s1, s95, 0
	v_writelane_b32 v244, s0, 17
	v_mov_b32_e32 v197, 0xf149f2ca
	v_mov_b64_e32 v[166:167], 0x400
	v_writelane_b32 v244, s1, 18
	s_add_i32 s0, 0, 0x20040
	v_mov_b64_e32 v[168:169], 0x3ff
	v_mov_b64_e32 v[170:171], 0x1600
	v_mov_b64_e32 v[172:173], 0x15ff
	v_mov_b32_e32 v198, 0x6000
	s_movk_i32 s85, 0xa00
	v_writelane_b32 v244, s0, 19
	s_add_i32 s0, 0, 0x20044
	s_mov_b32 s78, 0xf149f2ca
	s_movk_i32 s79, 0x1000
	s_movk_i32 s30, 0x1ff0
	s_movk_i32 s31, 0xfff
	s_movk_i32 s14, 0x1ff
	s_mov_b32 s15, 0x32001000
	s_mov_b32 s68, 0xc001000
	s_mov_b32 s69, 0x2a001000
	s_brev_b32 s4, 32
	s_mov_b32 s5, 0x4001000
	s_movk_i32 s33, 0xdf
	s_mov_b64 s[18:19], -1
	s_mov_b64 s[8:9], 0x80
	s_mov_b32 s28, 0x3e000000
	s_mov_b32 s26, 0x3fb8aa3b
	s_mov_b64 s[34:35], 0x10000
	s_mov_b64 s[66:67], 0x800
	s_mov_b32 s16, s77
	s_barrier
	v_writelane_b32 v244, s0, 20
	s_branch .LBB0_177
.LBB0_174:
	s_or_b64 exec, exec, s[18:19]
.LBB0_175:
	s_or_b64 exec, exec, s[0:1]
	s_mov_b64 s[0:1], 0
	s_waitcnt lgkmcnt(0)
	s_barrier

; __device__ __forceinline__ void xcd_barrier(const XcdBarrier& b) {
;     ...
;             asm volatile("s_waitcnt vmcnt(0)" ::: "memory");
;         }
;     }
;     __syncthreads();
; __device__ __forceinline__ void attn_phase(LAS unsigned char* lds, const bf16* PROJ, bf16* CONCAT, const float* sinks) {
;     ...
;     bf16x8 qf[4][2];
;     ...
;     const bool xmap = (gridDim.x == 256);
;     ...
;     if ((int)blockIdx.x < NB * 64 * 2) { ATT_LOAD_KV(ATT_UNIT((int)blockIdx.x)); ATT_LOAD_Q(ATT_UNIT((int)blockIdx.x)); }
.Lxb_norel_2:
.LBB0_260:
	s_or_b64 exec, exec, s[20:21]
.LBB0_261:
	s_or_b64 exec, exec, s[0:1]
	v_readlane_b32 s0, v244, 21
	v_readlane_b32 s1, v244, 22
	s_lshl_b32 s22, s0, 3
	v_readlane_b32 s0, v245, 30
	v_readlane_b32 s1, v245, 31
	s_xor_b64 s[20:21], s[18:19], -1
	v_mov_b32_e32 v70, v192
	v_cndmask_b32_e64 v0, 0, 1, s[0:1]
	v_cmp_ne_u32_e64 s[16:17], 1, v0
	s_andn2_b64 vcc, exec, s[0:1]
	s_waitcnt lgkmcnt(0)
	v_writelane_b32 v244, s16, 23
	s_barrier
	s_nop 0
	v_writelane_b32 v244, s17, 24
	s_cbranch_vccnz .LBB0_280
	v_ashrrev_i32_e32 v71, 6, v70
	v_readlane_b32 s16, v245, 32
	v_lshlrev_b32_e32 v68, 3, v71
	v_readlane_b32 s0, v245, 38
	v_readlane_b32 s17, v245, 33
	v_readlane_b32 s38, v245, 36
	v_ashrrev_i32_e32 v69, 31, v68
	v_readlane_b32 s1, v245, 39
	v_cndmask_b32_e64 v0, 0, 1, s[16:17]
	v_readlane_b32 s39, v245, 37
	v_and_b32_e32 v128, 63, v70
	v_lshl_add_u64 v[28:29], v[68:69], 1, s[0:1]
	v_cmp_ne_u32_e64 s[0:1], 1, v0
	s_andn2_b64 vcc, exec, s[16:17]
	s_mul_i32 s16, s39, 0xa00
	s_cbranch_vccnz .LBB0_265
	v_or_b32_e32 v0, s38, v128
	v_mad_u64_u32 v[2:3], s[36:37], v0, s85, v[28:29]
	v_add_u32_e32 v3, s16, v3
	global_load_dwordx4 v[4:7], v[2:3], off offset:1024
	global_load_dwordx4 v[8:11], v[2:3], off offset:1280
	s_and_b64 vcc, exec, s[0:1]
	v_or_b32_e32 v129, 64, v128
	s_cbranch_vccnz .LBB0_266

; #define PG8_STAGE(bufoff, gbase, voff) do { _Pragma("unroll") for (int _i = 0; _i < 2; ++_i) \
;         __builtin_amdgcn_global_load_lds((const unsigned*)((const char*)(gbase) + (voff)[_i]), (PG8_LAS unsigned*)(lds + (bufoff) + ldsw + _i * 8192), 16, 0, 0); } while (0)
; #define PG8_STAGEA(bufoff, gbase, voff) do { _Pragma("unroll") for (int _i = 0; _i < 2; ++_i) \
;         __builtin_amdgcn_global_load_lds((const unsigned*)((const char*)(gbase) + (voff)[_i]), (PG8_LAS unsigned*)(lds + (bufoff) + ldsw + _i * 8192), 16, 0, A_AUX); } while (0)
; #define PG8_WAIT_V(n) asm volatile("s_waitcnt vmcnt(" #n ")" ::: "memory")
; #define PG8_BAR __builtin_amdgcn_s_barrier()
;     ...
;     for (int i = 0; i < 2; ++i) { int R, C; stage_rc(tid * 16 + i * 8192, R, C); const int Rb = Epi::PERM ? ((R & ~31) + perm32(R & 31)) : R;
;         voffA[i] = (unsigned)(R * K + C) * 2u; voffB[i] = (unsigned)(Rb * K + C) * 2u; }
;     const size_t kstep = (size_t)(BK * 2);
;     const size_t hstep = (size_t)HALF * K * 2;
;     const size_t tstep = 2 * hstep;
;     const unsigned ldsw = (unsigned)wid * 1024u;
;     const int aoff = lds_byte(wr * 64 + fr, fq * 8), boff = lds_byte(wc * 32 + fr, fq * 8);
;     ...
;     if constexpr (SP2) {
;         PG8_STAGE(PG8_SB(0, 0), cB, voffB); PG8_STAGE(PG8_SB(0, 1), cB + hstep, voffB); PG8_STAGEA(PG8_SA(0, 0), cA, voffA); PG8_STAGEA(PG8_SA(0, 1), cA + hstep, voffA);
;         if (wr == 1) PG8_BAR;
;         PG8_WAIT_V(2); PG8_BAR;
;         PG8_STAGE(PG8_SB(1, 0), cB + kstep, voffB); PG8_STAGEA(PG8_SA(1, 0), cA + kstep, voffA); PG8_STAGE(PG8_SB(1, 1), cB + hstep + kstep, voffB);
;         PG8_WAIT_V(6); PG8_BAR;
.Lxb_norel_3:
.LBB0_429:
	s_or_b64 exec, exec, s[36:37]
.LBB0_430:
	s_or_b64 exec, exec, s[0:1]
	v_readlane_b32 s0, v244, 23
	s_waitcnt vmcnt(7)
	v_mov_b32_e32 v8, v192
	v_readlane_b32 s1, v244, 24
	s_waitcnt lgkmcnt(0)
	s_barrier
	s_and_b64 vcc, exec, s[0:1]
	v_readfirstlane_b32 s16, v8
	s_cbranch_vccnz .LBB0_450
	v_lshlrev_b32_e32 v0, 4, v8
	v_add_u32_e32 v3, 0x2000, v0
	v_ashrrev_i32_e32 v2, 31, v3
	v_lshrrev_b32_e32 v2, 22, v2
	v_add_u32_e32 v2, v3, v2
	v_ashrrev_i32_e32 v2, 10, v2
	v_mul_i32_i24_e32 v4, 0x400, v2
	v_sub_u32_e32 v3, v3, v4
	v_lshrrev_b32_e32 v4, 4, v3
	v_bitop3_b32 v4, v4, v3, 32 bitop3:0x6c
	v_ashrrev_i32_e32 v3, 31, v4
	v_lshrrev_b32_e32 v3, 26, v3
	v_add_u32_e32 v5, v4, v3
	v_lshlrev_b32_e32 v6, 3, v2
	v_readlane_b32 s0, v246, 9
	v_ashrrev_i32_e32 v3, 6, v5
	v_and_b32_e32 v6, -16, v6
	s_add_u32 s23, s0, 0x300000
	v_readlane_b32 s0, v246, 6
	v_add_u32_e32 v6, v3, v6
	s_addc_u32 s54, s0, 0
	v_and_b32_e32 v7, 3, v3
	s_mov_b32 s0, 0x1fffe0
	v_lshrrev_b32_e32 v9, 2, v6
	s_waitcnt vmcnt(6)
	v_lshlrev_b32_e32 v10, 1, v6
	v_and_b32_e32 v5, 0xc0, v5
	v_and_or_b32 v7, v6, s0, v7
	v_and_b32_e32 v9, 4, v9
	v_and_b32_e32 v10, 24, v10
	v_sub_u32_e32 v4, v4, v5
	v_or3_b32 v7, v7, v9, v10
	v_lshlrev_b32_e32 v9, 5, v2
	v_ashrrev_i16_sdwa v4, v193, sext(v4) dst_sel:DWORD dst_unused:UNUSED_PAD src0_sel:DWORD src1_sel:BYTE_0
	v_and_b32_e32 v9, 32, v9
	v_bfe_i32 v4, v4, 0, 16
	v_add_lshl_u32 v5, v9, v4, 1
	v_lshl_add_u32 v130, v7, 11, v5
	v_lshl_add_u32 v132, v6, 11, v5
	v_bfe_i32 v5, v8, 27, 1
	v_lshrrev_b32_e32 v5, 22, v5
	v_add_u32_e32 v5, v0, v5
	v_and_b32_e32 v5, 0xfffffc00, v5
	v_sub_u32_e32 v0, v0, v5
	v_lshrrev_b32_e32 v5, 4, v0
	v_ashrrev_i32_e32 v6, 31, v8
	v_bitop3_b32 v0, v5, v0, 32 bitop3:0x6c
	v_lshrrev_b32_e32 v6, 26, v6
	v_ashrrev_i32_e32 v5, 31, v0
	v_add_u32_e32 v6, v8, v6
	v_lshrrev_b32_e32 v5, 26, v5
	v_ashrrev_i32_e32 v6, 6, v6
	v_add_u32_e32 v7, v0, v5
	v_lshlrev_b32_e32 v9, 3, v6
	v_ashrrev_i32_e32 v5, 6, v7
	v_and_b32_e32 v9, -16, v9
	v_add_u32_e32 v9, v5, v9
	v_and_b32_e32 v10, 3, v5
	v_lshrrev_b32_e32 v11, 2, v9
	v_lshlrev_b32_e32 v12, 1, v9
	v_and_b32_e32 v7, 0xc0, v7
	s_ashr_i32 s17, s16, 6
	v_and_or_b32 v10, v9, s0, v10
	v_and_b32_e32 v11, 4, v11
	v_and_b32_e32 v12, 24, v12
	v_sub_u32_e32 v0, v0, v7
	s_ashr_i32 s36, s16, 8
	s_lshl_b32 s55, s17, 10
	v_or3_b32 v10, v10, v11, v12
	v_lshlrev_b32_e32 v11, 5, v6
	v_ashrrev_i16_sdwa v0, v193, sext(v0) dst_sel:DWORD dst_unused:UNUSED_PAD src0_sel:DWORD src1_sel:BYTE_0
	v_readlane_b32 s0, v245, 50
	v_and_b32_e32 v11, 32, v11
	v_bfe_i32 v7, v0, 0, 16
	v_readlane_b32 s1, v245, 51
	s_add_u32 s50, s23, s0
	v_add_lshl_u32 v11, v11, v7, 1
	s_addc_u32 s51, s54, s1
	s_add_i32 s56, s55, 0
	v_lshl_add_u32 v0, v10, 11, v11
	s_add_i32 m0, s56, 0x10000
	v_lshl_add_u32 v134, v9, 11, v11
	global_load_lds_dwordx4 v0, s[50:51]
	s_add_i32 m0, s56, 0x12000
	s_add_u32 s0, s50, 0x40000
	global_load_lds_dwordx4 v130, s[50:51]
	s_addc_u32 s1, s51, 0
	s_add_i32 m0, s56, 0x14000
	s_add_i32 s57, s56, 0x2000
	global_load_lds_dwordx4 v0, s[0:1]
	s_add_i32 m0, s56, 0x16000
	s_add_i32 s58, s56, 0x4000
	global_load_lds_dwordx4 v130, s[0:1]
	v_readlane_b32 s0, v245, 52
	s_mov_b32 m0, s56
	v_readlane_b32 s1, v245, 53
	s_add_i32 s59, s56, 0x6000
	s_cmp_eq_u32 s36, 1
	s_nop 2
	global_load_lds_dwordx4 v134, s[0:1]
	s_mov_b32 m0, s57
	s_nop 0
	global_load_lds_dwordx4 v132, s[0:1]
	v_readlane_b32 s0, v245, 54
	s_mov_b32 m0, s58
	v_readlane_b32 s1, v245, 55
	s_nop 4
	global_load_lds_dwordx4 v134, s[0:1]
	s_mov_b32 m0, s59
	s_nop 0
	global_load_lds_dwordx4 v132, s[0:1]
	s_cselect_b64 s[0:1], -1, 0
	s_cmp_lg_u32 s36, 1
	s_cbranch_scc1 .LBB0_433
	s_barrier

; __device__ __forceinline__ void rowwise_phase(const Args& a, LAS unsigned char* lds, bool from_partials, bool has_y, bool has_h, bool xin_bf, int xout_mode, ...
;     ...
;     for (int tile = blockIdx.x; tile < T / 256; tile += gridDim.x) {
;         const int b = tile / (SEQ / 256);
;         __syncthreads();
;         for (int col = tid; col < DM; col += 512) {
;             if (from_partials) {
;                 if (has_y) vec[col] = mod_val(a, l_y, b, gate_idx, col) * g_post[col];
;                 if (has_h) { vec[DM + col] = g_pre[col] * (1.0f + mod_val(a, l_h, b, scale_idx, col)); vec[2 * DM + col] = mod_val(a, l_h, b, shift_idx, col); }
;             } else {
;                 if (has_y) vec[col] = mod_fin(a, l_y, b, gate_idx, col) * g_post[col];
;                 if (has_h) { vec[DM + col] = g_pre[col] * (1.0f + mod_fin(a, l_h, b, scale_idx, col)); vec[2 * DM + col] = mod_fin(a, l_h, b, shift_idx, col); }
;             }
;         }
;         __syncthreads();
.Lxb_norel_4:
.LBB0_501:
	s_or_b64 exec, exec, s[36:37]
.LBB0_502:
	s_or_b64 exec, exec, s[0:1]
	v_readlane_b32 s0, v246, 7
	v_readlane_b32 s1, v246, 8
	s_waitcnt lgkmcnt(0)
	v_mov_b32_e32 v2, v192
	s_andn2_b64 vcc, exec, s[0:1]
	v_cndmask_b32_e64 v0, 0, 1, s[0:1]
	v_cmp_ne_u32_e64 s[38:39], 1, v0
	s_barrier
	s_cbranch_vccnz .LBB0_519
	v_readlane_b32 s40, v246, 11
	v_readlane_b32 s0, v244, 21
	v_readlane_b32 s48, v246, 19
	v_readlane_b32 s49, v246, 20
	v_readlane_b32 s50, v246, 21
	v_readlane_b32 s51, v246, 22
	v_readlane_b32 s52, v246, 23
	v_readlane_b32 s53, v246, 24
	v_readlane_b32 s1, v244, 22
	s_lshl_b32 s76, s0, 10
	v_readlane_b32 s54, v246, 25
	v_readlane_b32 s55, v246, 26
	s_mov_b64 s[48:49], s[52:53]
	s_lshl_b64 s[0:1], s[76:77], 2
	s_mov_b64 s[50:51], s[54:55]
	v_ashrrev_i32_e32 v3, 4, v2
	s_add_u32 s48, s50, s0
	v_and_b32_e32 v6, -4, v3
	v_max_i32_e32 v3, 0x200, v2
	s_addc_u32 s49, s51, s1
	v_sub_u32_e32 v3, v3, v2
	v_readlane_b32 s41, v246, 12
	s_add_u32 s50, s88, s0
	s_movk_i32 s0, 0x400
	v_add_u32_e32 v3, 0x1ff, v3
	v_lshlrev_b32_e32 v12, 2, v2
	v_readlane_b32 s42, v246, 13
	v_readlane_b32 s43, v246, 14
	v_cmp_gt_i32_e64 s[40:41], s0, v2
	s_movk_i32 s0, 0x100
	v_lshrrev_b32_e32 v4, 9, v3
	v_add_u32_e32 v13, 0, v12
	v_readlane_b32 s44, v246, 15
	v_readlane_b32 s45, v246, 16
	v_cmp_gt_i32_e64 s[42:43], s0, v6
	v_add_u32_e32 v9, 1, v4
	s_movk_i32 s0, 0x2dff
	v_lshl_add_u32 v4, v4, 11, v13
	v_readlane_b32 s46, v246, 17
	v_readlane_b32 s47, v246, 18
	v_add_u32_e32 v5, 0x1000, v13
	v_add_u32_e32 v7, 0x2000, v13
	v_cmp_lt_u32_e32 vcc, s0, v3
	v_add_u32_e32 v10, 0x1000, v4
	v_cmp_gt_u32_e64 s[44:45], 2.0, v3
	v_add_u32_e32 v3, 0x2000, v4
	s_addc_u32 s51, s89, s1
	v_cmp_lt_u32_e64 s[0:1], v10, v5
	v_cmp_lt_u32_e64 s[46:47], v3, v7
	s_or_b64 s[0:1], s[46:47], s[0:1]
	v_and_b32_e32 v0, 63, v2
	s_xor_b64 s[0:1], s[0:1], -1
	v_lshlrev_b32_e32 v8, 5, v0
	s_and_b64 s[0:1], s[0:1], s[44:45]
	v_and_b32_e32 v14, 0xfffffe, v9
	v_lshlrev_b32_e32 v0, 4, v0
	v_ashrrev_i32_e32 v7, 31, v6
	v_lshl_add_u32 v15, v14, 9, v2
	v_add_u32_e32 v3, 0x200, v2
	v_cmp_ne_u32_e64 s[44:45], v9, v14
	s_and_b64 s[0:1], vcc, s[0:1]
	v_subrev_u32_e32 v16, 32, v6
	v_lshl_add_u64 v[4:5], s[94:95], 0, v[0:1]
	v_lshlrev_b64 v[6:7], 11, v[6:7]
	v_add_u32_e32 v0, 0, v8
	s_mov_b32 s46, s2
	v_readlane_b32 s64, v245, 42
	v_readlane_b32 s65, v245, 43
	s_branch .LBB0_505

; #define PG8_STAGE(bufoff, gbase, voff) do { _Pragma("unroll") for (int _i = 0; _i < 2; ++_i) \
;         __builtin_amdgcn_global_load_lds((const unsigned*)((const char*)(gbase) + (voff)[_i]), (PG8_LAS unsigned*)(lds + (bufoff) + ldsw + _i * 8192), 16, 0, 0); } while (0)
; #define PG8_STAGEA(bufoff, gbase, voff) do { _Pragma("unroll") for (int _i = 0; _i < 2; ++_i) \
;         __builtin_amdgcn_global_load_lds((const unsigned*)((const char*)(gbase) + (voff)[_i]), (PG8_LAS unsigned*)(lds + (bufoff) + ldsw + _i * 8192), 16, 0, A_AUX); } while (0)
; #define PG8_WAIT_V(n) asm volatile("s_waitcnt vmcnt(" #n ")" ::: "memory")
; #define PG8_BAR __builtin_amdgcn_s_barrier()
;     ...
;     for (int i = 0; i < 2; ++i) { int R, C; stage_rc(tid * 16 + i * 8192, R, C); const int Rb = Epi::PERM ? ((R & ~31) + perm32(R & 31)) : R;
;         voffA[i] = (unsigned)(R * K + C) * 2u; voffB[i] = (unsigned)(Rb * K + C) * 2u; }
;     const size_t kstep = (size_t)(BK * 2);
;     const size_t hstep = (size_t)HALF * K * 2;
;     const size_t tstep = 2 * hstep;
;     const unsigned ldsw = (unsigned)wid * 1024u;
;     const int aoff = lds_byte(wr * 64 + fr, fq * 8), boff = lds_byte(wc * 32 + fr, fq * 8);
;     ...
;     if constexpr (SP2) {
;         PG8_STAGE(PG8_SB(0, 0), cB, voffB); PG8_STAGE(PG8_SB(0, 1), cB + hstep, voffB); PG8_STAGEA(PG8_SA(0, 0), cA, voffA); PG8_STAGEA(PG8_SA(0, 1), cA + hstep, voffA);
;         if (wr == 1) PG8_BAR;
;         PG8_WAIT_V(2); PG8_BAR;
;         PG8_STAGE(PG8_SB(1, 0), cB + kstep, voffB); PG8_STAGEA(PG8_SA(1, 0), cA + kstep, voffA); PG8_STAGE(PG8_SB(1, 1), cB + hstep + kstep, voffB);
;         PG8_WAIT_V(6); PG8_BAR;
.Lxb_norel_5:
.LBB0_570:
	s_or_b64 exec, exec, s[36:37]
.LBB0_571:
	s_or_b64 exec, exec, s[0:1]
	v_readlane_b32 s0, v245, 44
	v_mov_b32_e32 v8, v192
	v_readlane_b32 s1, v245, 45
	s_waitcnt lgkmcnt(0)
	s_barrier
	s_andn2_b64 vcc, exec, s[0:1]
	v_readfirstlane_b32 s16, v8
	s_cbranch_vccnz .LBB0_587
	v_lshlrev_b32_e32 v0, 4, v8
	v_add_u32_e32 v3, 0x2000, v0
	v_ashrrev_i32_e32 v2, 31, v3
	v_lshrrev_b32_e32 v2, 22, v2
	v_add_u32_e32 v2, v3, v2
	v_ashrrev_i32_e32 v2, 10, v2
	v_mul_i32_i24_e32 v4, 0x400, v2
	v_sub_u32_e32 v3, v3, v4
	v_lshrrev_b32_e32 v4, 4, v3
	v_bitop3_b32 v4, v4, v3, 32 bitop3:0x6c
	v_ashrrev_i32_e32 v3, 31, v4
	v_lshrrev_b32_e32 v3, 26, v3
	v_add_u32_e32 v5, v4, v3
	v_lshlrev_b32_e32 v6, 3, v2
	v_readlane_b32 s0, v246, 9
	v_ashrrev_i32_e32 v3, 6, v5
	v_and_b32_e32 v6, -16, v6
	s_add_u32 s23, s0, 0x500000
	v_readlane_b32 s0, v246, 6
	v_add_u32_e32 v6, v3, v6
	s_addc_u32 s56, s0, 0
	v_and_b32_e32 v7, 3, v3
	s_mov_b32 s0, 0x1fffe0
	v_lshrrev_b32_e32 v9, 2, v6
	v_lshlrev_b32_e32 v10, 1, v6
	v_and_b32_e32 v5, 0xc0, v5
	v_and_or_b32 v7, v6, s0, v7
	v_and_b32_e32 v9, 4, v9
	v_and_b32_e32 v10, 24, v10
	v_sub_u32_e32 v4, v4, v5
	v_or3_b32 v7, v7, v9, v10
	v_lshlrev_b32_e32 v9, 5, v2
	v_ashrrev_i16_sdwa v4, v193, sext(v4) dst_sel:DWORD dst_unused:UNUSED_PAD src0_sel:DWORD src1_sel:BYTE_0
	v_and_b32_e32 v9, 32, v9
	v_bfe_i32 v4, v4, 0, 16
	v_add_lshl_u32 v5, v9, v4, 1
	v_lshl_add_u32 v130, v7, 11, v5
	v_lshl_add_u32 v132, v6, 11, v5
	v_bfe_i32 v5, v8, 27, 1
	v_lshrrev_b32_e32 v5, 22, v5
	v_add_u32_e32 v5, v0, v5
	v_and_b32_e32 v5, 0xfffffc00, v5
	v_sub_u32_e32 v0, v0, v5
	v_lshrrev_b32_e32 v5, 4, v0
	v_ashrrev_i32_e32 v6, 31, v8
	v_bitop3_b32 v0, v5, v0, 32 bitop3:0x6c
	v_lshrrev_b32_e32 v6, 26, v6
	v_ashrrev_i32_e32 v5, 31, v0
	v_add_u32_e32 v6, v8, v6
	v_lshrrev_b32_e32 v5, 26, v5
	v_ashrrev_i32_e32 v6, 6, v6
	v_add_u32_e32 v7, v0, v5
	v_lshlrev_b32_e32 v9, 3, v6
	v_ashrrev_i32_e32 v5, 6, v7
	v_and_b32_e32 v9, -16, v9
	v_add_u32_e32 v9, v5, v9
	v_and_b32_e32 v10, 3, v5
	v_lshrrev_b32_e32 v11, 2, v9
	v_lshlrev_b32_e32 v12, 1, v9
	v_and_b32_e32 v7, 0xc0, v7
	s_ashr_i32 s17, s16, 6
	v_and_or_b32 v10, v9, s0, v10
	v_and_b32_e32 v11, 4, v11
	v_and_b32_e32 v12, 24, v12
	v_sub_u32_e32 v0, v0, v7
	s_ashr_i32 s36, s16, 8
	s_lshl_b32 s57, s17, 10
	v_or3_b32 v10, v10, v11, v12
	v_lshlrev_b32_e32 v11, 5, v6
	v_ashrrev_i16_sdwa v0, v193, sext(v0) dst_sel:DWORD dst_unused:UNUSED_PAD src0_sel:DWORD src1_sel:BYTE_0
	v_readlane_b32 s0, v245, 59
	v_and_b32_e32 v11, 32, v11
	v_bfe_i32 v7, v0, 0, 16
	v_readlane_b32 s1, v245, 60
	s_add_u32 s52, s23, s0
	v_add_lshl_u32 v11, v11, v7, 1
	s_addc_u32 s53, s56, s1
	s_add_i32 s58, s57, 0
	v_lshl_add_u32 v0, v10, 11, v11
	s_add_i32 m0, s58, 0x10000
	v_lshl_add_u32 v134, v9, 11, v11
	global_load_lds_dwordx4 v0, s[52:53]
	s_add_i32 m0, s58, 0x12000
	s_add_u32 s0, s52, 0x40000
	global_load_lds_dwordx4 v130, s[52:53]
	s_addc_u32 s1, s53, 0
	s_add_i32 m0, s58, 0x14000
	s_add_i32 s59, s58, 0x2000
	global_load_lds_dwordx4 v0, s[0:1]
	s_add_i32 m0, s58, 0x16000
	s_add_i32 s60, s58, 0x4000
	global_load_lds_dwordx4 v130, s[0:1]
	v_readlane_b32 s0, v245, 61
	s_mov_b32 m0, s58
	v_readlane_b32 s1, v245, 62
	s_add_i32 s61, s58, 0x6000
	s_cmp_eq_u32 s36, 1
	s_nop 2
	global_load_lds_dwordx4 v134, s[0:1]
	s_mov_b32 m0, s59
	s_nop 0
	global_load_lds_dwordx4 v132, s[0:1]
	v_readlane_b32 s0, v245, 63
	s_mov_b32 m0, s60
	v_readlane_b32 s1, v244, 0
	s_nop 4
	global_load_lds_dwordx4 v134, s[0:1]
	s_mov_b32 m0, s61
	s_nop 0
	global_load_lds_dwordx4 v132, s[0:1]
	s_cselect_b64 s[0:1], -1, 0
	s_cmp_lg_u32 s36, 1
	s_cbranch_scc1 .LBB0_574
	s_barrier

; #define PG8_WAIT_V(n) asm volatile("s_waitcnt vmcnt(" #n ")" ::: "memory")
; #define PG8_BAR __builtin_amdgcn_s_barrier()
;     int tid_ = threadIdx.x; asm volatile("" : "+v"(tid_)); const int tid = tid_, wid = __builtin_amdgcn_readfirstlane(tid >> 6), lane = tid & 63, wr = wid >> 2, wc = wid & 3, fr = lane & 15, fq = lane >> 4;
;     const int K = g.K, nt = K / BK;
;     unsigned voffA[2], voffB[2];
; #pragma unroll
;     for (int i = 0; i < 2; ++i) { int R, C; stage_rc(tid * 16 + i * 8192, R, C); const int Rb = Epi::PERM ? ((R & ~31) + perm32(R & 31)) : R;
;         voffA[i] = (unsigned)(R * K + C) * 2u; voffB[i] = (unsigned)(Rb * K + C) * 2u; }
;     const size_t kstep = (size_t)(BK * 2);
;     const size_t hstep = (size_t)HALF * K * 2;
;     const size_t tstep = 2 * hstep;
;     const unsigned ldsw = (unsigned)wid * 1024u;
;     const int aoff = lds_byte(wr * 64 + fr, fq * 8), boff = lds_byte(wc * 32 + fr, fq * 8);
;     ...
;     Unit cur, nxt; int ui = 0;
;     if (!S.next(0, cur)) return;
;     f32x4 acc[2][2][4][2];
; #pragma unroll
;     for (int a = 0; a < 2; ++a)
; #pragma unroll
;         for (int b = 0; b < 2; ++b)
; #pragma unroll
;             for (int m = 0; m < 4; ++m)
; #pragma unroll
;                 for (int n = 0; n < 2; ++n) acc[a][b][m][n] = (f32x4){0.f, 0.f, 0.f, 0.f};
;     bf16x8 At[4][2], B0[2][2], B1[2][2];
;     const char* cA = (const char*)g.A + (size_t)cur.pm * tstep; const char* cB = (const char*)g.Bt + (size_t)cur.pn * tstep;
;     S.a_ready(cur);
;     if constexpr (SP2) {
;         PG8_STAGE(PG8_SB(0, 0), cB, voffB); PG8_STAGE(PG8_SB(0, 1), cB + hstep, voffB); PG8_STAGEA(PG8_SA(0, 0), cA, voffA); PG8_STAGEA(PG8_SA(0, 1), cA + hstep, voffA);
;         if (wr == 1) PG8_BAR;
;         PG8_WAIT_V(2); PG8_BAR;
;         PG8_STAGE(PG8_SB(1, 0), cB + kstep, voffB); PG8_STAGEA(PG8_SA(1, 0), cA + kstep, voffA); PG8_STAGE(PG8_SB(1, 1), cB + hstep + kstep, voffB);
;         PG8_WAIT_V(6); PG8_BAR;
;     } else {
; __device__ __forceinline__ void xcd_barrier(const XcdBarrier& b) {
;     ...
;             xb_add(&bar[XB_XGEN(b.x)], 1u);
;             asm volatile("s_waitcnt vmcnt(0)" ::: "memory");
;         } else {
;             XB_SPIN(xb_ld(&bar[XB_XGEN(b.x)]) == gen, bar);
;             __builtin_amdgcn_fence(__ATOMIC_ACQUIRE, "agent");
;             asm volatile("s_waitcnt vmcnt(0)" ::: "memory");
;         }
;     }
;     __syncthreads();
.Lxb_norel_6:
.LBB0_638:
	s_or_b64 exec, exec, s[36:37]
.LBB0_639:
	s_or_b64 exec, exec, s[0:1]
	v_readlane_b32 s0, v244, 23
	v_mov_b32_e32 v14, v192
	v_readlane_b32 s1, v244, 24
	s_waitcnt lgkmcnt(0)
	s_barrier
	s_and_b64 vcc, exec, s[0:1]
	v_readfirstlane_b32 s0, v14
	s_cbranch_vccnz .LBB0_663
	v_lshlrev_b32_e32 v0, 4, v14
	v_add_u32_e32 v2, 0x2000, v0
	v_ashrrev_i32_e32 v3, 31, v2
	v_lshrrev_b32_e32 v3, 22, v3
	v_add_u32_e32 v3, v2, v3
	v_ashrrev_i32_e32 v6, 10, v3
	v_mul_i32_i24_e32 v3, 0x400, v6
	v_sub_u32_e32 v2, v2, v3
	v_lshrrev_b32_e32 v3, 4, v2
	v_bitop3_b32 v2, v3, v2, 32 bitop3:0x6c
	v_ashrrev_i32_e32 v3, 31, v2
	v_lshrrev_b32_e32 v3, 26, v3
	v_add_u32_e32 v3, v2, v3
	v_lshlrev_b32_e32 v4, 3, v6
	v_ashrrev_i32_e32 v7, 6, v3
	v_and_b32_e32 v4, -16, v4
	v_add_u32_e32 v4, v7, v4
	v_and_b32_e32 v5, 3, v7
	s_mov_b32 s17, 0xffffe0
	v_lshrrev_b32_e32 v8, 2, v4
	v_lshlrev_b32_e32 v9, 1, v4
	v_and_b32_e32 v3, 0xc0, v3
	v_and_or_b32 v5, v4, s17, v5
	v_and_b32_e32 v8, 4, v8
	v_and_b32_e32 v9, 24, v9
	v_sub_u32_e32 v2, v2, v3
	v_or3_b32 v5, v5, v8, v9
	v_lshlrev_b32_e32 v8, 5, v6
	v_ashrrev_i16_sdwa v2, v193, sext(v2) dst_sel:DWORD dst_unused:UNUSED_PAD src0_sel:DWORD src1_sel:BYTE_0
	v_and_b32_e32 v8, 32, v8
	v_bfe_i32 v9, v2, 0, 16
	s_movk_i32 s36, 0xb00
	v_mul_u32_u24_e32 v5, 0xb00, v5
	v_add_u32_e32 v2, v8, v9
	v_mul_lo_u32 v3, v4, s36
	v_add_lshl_u32 v130, v5, v2, 1
	v_add_lshl_u32 v132, v2, v3, 1
	v_bfe_i32 v2, v14, 27, 1
	v_lshrrev_b32_e32 v2, 22, v2
	v_add_u32_e32 v2, v0, v2
	v_and_b32_e32 v2, 0xfffffc00, v2
	v_sub_u32_e32 v0, v0, v2
	v_lshrrev_b32_e32 v2, 4, v0
	v_ashrrev_i32_e32 v3, 31, v14
	v_bitop3_b32 v0, v2, v0, 32 bitop3:0x6c
	v_lshrrev_b32_e32 v3, 26, v3
	v_ashrrev_i32_e32 v2, 31, v0
	v_add_u32_e32 v3, v14, v3
	v_lshrrev_b32_e32 v2, 26, v2
	v_ashrrev_i32_e32 v11, 6, v3
	v_add_u32_e32 v2, v0, v2
	v_lshlrev_b32_e32 v3, 3, v11
	v_ashrrev_i32_e32 v10, 6, v2
	v_and_b32_e32 v3, -16, v3
	v_readlane_b32 s1, v246, 9
	v_add_u32_e32 v3, v10, v3
	s_add_u32 s23, s1, 0x1000000
	v_readlane_b32 s1, v246, 6
	v_and_b32_e32 v4, 3, v10
	v_lshrrev_b32_e32 v5, 2, v3
	v_lshlrev_b32_e32 v12, 1, v3
	v_and_b32_e32 v2, 0xc0, v2
	s_addc_u32 s54, s1, 0
	s_ashr_i32 s1, s0, 6
	v_and_or_b32 v4, v3, s17, v4
	v_and_b32_e32 v5, 4, v5
	v_and_b32_e32 v12, 24, v12
	v_sub_u32_e32 v0, v0, v2
	v_mul_lo_u32 v3, v3, s36
	v_readlane_b32 s36, v245, 47
	s_ashr_i32 s16, s0, 8
	s_lshl_b32 s55, s1, 10
	v_or3_b32 v4, v4, v5, v12
	v_lshlrev_b32_e32 v5, 5, v11
	v_ashrrev_i16_sdwa v0, v193, sext(v0) dst_sel:DWORD dst_unused:UNUSED_PAD src0_sel:DWORD src1_sel:BYTE_0
	s_mul_i32 s17, s36, 0x160000
	v_and_b32_e32 v12, 32, v5
	v_bfe_i32 v13, v0, 0, 16
	s_add_u32 s48, s23, s17
	s_mul_hi_i32 s17, s36, 0x160000
	v_mul_u32_u24_e32 v4, 0xb00, v4
	v_add_u32_e32 v2, v12, v13
	s_addc_u32 s49, s54, s17
	s_add_i32 s56, s55, 0
	v_add_lshl_u32 v0, v4, v2, 1
	s_add_i32 m0, s56, 0x10000
	v_add_lshl_u32 v134, v2, v3, 1
	global_load_lds_dwordx4 v0, s[48:49]
	s_add_i32 m0, s56, 0x12000
	s_add_u32 s36, s48, 0xb0000
	global_load_lds_dwordx4 v130, s[48:49]
	s_addc_u32 s37, s49, 0
	s_add_i32 m0, s56, 0x14000
	s_add_i32 s57, s56, 0x2000
	global_load_lds_dwordx4 v0, s[36:37]
	s_add_i32 m0, s56, 0x16000
	s_add_i32 s58, s56, 0x4000
	global_load_lds_dwordx4 v130, s[36:37]
	v_readlane_b32 s36, v244, 2
	s_mov_b32 m0, s56
	v_readlane_b32 s37, v244, 3
	s_add_i32 s59, s56, 0x6000
	v_mov_b32_e32 v131, v1
	s_cmp_eq_u32 s16, 1
	v_lshl_add_u64 v[2:3], s[48:49], 0, v[0:1]
	s_cselect_b64 s[40:41], -1, 0
	global_load_lds_dwordx4 v134, s[36:37]
	s_mov_b32 m0, s57
	s_cmp_lg_u32 s16, 1
	global_load_lds_dwordx4 v132, s[36:37]
	v_readlane_b32 s36, v244, 4
	s_mov_b32 m0, s58
	v_readlane_b32 s37, v244, 5
	v_lshl_add_u64 v[4:5], s[48:49], 0, v[130:131]
	s_nop 3
	global_load_lds_dwordx4 v134, s[36:37]
	s_mov_b32 m0, s59
	s_nop 0
	global_load_lds_dwordx4 v132, s[36:37]
	s_cbranch_scc1 .LBB0_642
	s_barrier

; __device__ __forceinline__ unsigned xb_ld(unsigned* p)              { return __hip_atomic_load(p, __ATOMIC_RELAXED, __HIP_MEMORY_SCOPE_AGENT); }
; #define XB_SPIN(cond, bar) do { unsigned _sp = 0; while (cond) { __builtin_amdgcn_s_sleep(1); \
;     if ((++_sp & 255u) == 0u) { if (xb_ld(&(bar)[XB_TMO])) break; if (_sp > XB_SPIN_CAP) { atomicAdd(&(bar)[XB_TMO], 1u); break; } } } } while (0)
; #define SEAM() do { for (int rs_ = 0; rs_ < REP_S; ++rs_) xcd_barrier(bar); } while (0)
; __device__ __forceinline__ void xcd_barrier(const XcdBarrier& b) {
;     ...
;             XB_SPIN(xb_ld(&bar[XB_XGEN(b.x)]) == gen, bar);
;             __builtin_amdgcn_fence(__ATOMIC_ACQUIRE, "agent");
;             asm volatile("s_waitcnt vmcnt(0)" ::: "memory");
;         }
;     }
;     __syncthreads();
; }
; __global__ void __launch_bounds__(512, 2) fwd_kernel(Args a) {
;     ...
;         const bool more = (l + 1 < DEPTH);
;         for (int rep = 0; rep < REP_R; ++rep) rowwise_phase(a, lds, false, true, more, true, more ? 2 : 1, XA, MIX, a.out, XB, H, l, 5, a.g_post_ffn + l * DM, l + 1, 0, 1, a.g_pre_mix + (more ? (l + 1) * DM : 0));
;         if (more) SEAM();
;     }
.Lxb_norel_7:
.LBB0_714:
	s_or_b64 exec, exec, s[36:37]
.LBB0_715:
	s_or_b64 exec, exec, s[0:1]
	s_waitcnt lgkmcnt(0)
	v_mov_b32_e32 v2, v192
	s_and_b64 vcc, exec, s[38:39]
	s_barrier
	s_cbranch_vccz .LBB0_717
	s_andn2_b64 vcc, exec, s[18:19]
	s_mov_b64 s[0:1], -1
	s_cbranch_vccnz .LBB0_176
	s_branch .LBB0_734
